# up-projection epilogue de-serialisation: the two full vmcnt drains that only waited for this wave's own result stores (between the two feature groups, and before the boundary-row stores) are removed
# speedup vs baseline: 1.0025x; 1.0025x over previous
.LBB0_619:
	s_or_b64 exec, exec, s[0:1]
	v_or_b32_e32 v130, 4, v176
	v_ashrrev_i32_e32 v131, 31, v130
	v_readlane_b32 s0, v254, 21
	v_lshlrev_b64 v[142:143], 2, v[130:131]
	v_readlane_b32 s1, v254, 22
	global_load_dwordx4 v[146:149], v[180:181], off offset:16
	v_lshl_add_u64 v[132:133], s[68:69], 0, v[142:143]
	v_lshl_add_u64 v[130:131], s[0:1], 0, v[142:143]
	global_load_dwordx4 v[150:153], v[130:131], off
	global_load_dwordx4 v[154:157], v[132:133], off
	global_load_dwordx4 v[158:161], v[182:183], off offset:16
	v_lshl_add_u64 v[130:131], s[70:71], 0, v[142:143]
	v_lshl_add_u64 v[134:135], s[72:73], 0, v[142:143]
	v_lshl_add_u64 v[138:139], s[74:75], 0, v[142:143]
	v_lshl_add_u64 v[142:143], s[76:77], 0, v[142:143]
	global_load_dwordx4 v[130:133], v[130:131], off
	s_nop 0
	global_load_dwordx4 v[134:137], v[134:135], off
	v_mov_b32_dpp v194, v56 row_shr:2 row_mask:0xf bank_mask:0xf bound_ctrl:1
	global_load_dwordx4 v[138:141], v[138:139], off
	v_mov_b32_dpp v192, v56 row_shr:1 row_mask:0xf bank_mask:0xf bound_ctrl:1
	global_load_dwordx4 v[142:145], v[142:143], off
	v_mov_b32_dpp v190, v122 row_shr:2 row_mask:0xf bank_mask:0xf bound_ctrl:1
	v_mov_b32_dpp v188, v122 row_shr:1 row_mask:0xf bank_mask:0xf bound_ctrl:1
	v_mov_b32_dpp v195, v57 row_shr:2 row_mask:0xf bank_mask:0xf bound_ctrl:1
	v_mov_b32_dpp v193, v57 row_shr:1 row_mask:0xf bank_mask:0xf bound_ctrl:1
	v_mov_b32_dpp v191, v123 row_shr:2 row_mask:0xf bank_mask:0xf bound_ctrl:1
	v_mov_b32_dpp v189, v123 row_shr:1 row_mask:0xf bank_mask:0xf bound_ctrl:1
	v_mov_b32_dpp v186, v58 row_shr:2 row_mask:0xf bank_mask:0xf bound_ctrl:1
	v_mov_b32_dpp v184, v58 row_shr:1 row_mask:0xf bank_mask:0xf bound_ctrl:1
	v_mov_b32_dpp v182, v124 row_shr:2 row_mask:0xf bank_mask:0xf bound_ctrl:1
	v_mov_b32_dpp v180, v124 row_shr:1 row_mask:0xf bank_mask:0xf bound_ctrl:1
	v_mov_b32_dpp v187, v59 row_shr:2 row_mask:0xf bank_mask:0xf bound_ctrl:1
	v_mov_b32_dpp v185, v59 row_shr:1 row_mask:0xf bank_mask:0xf bound_ctrl:1
	v_mov_b32_dpp v183, v125 row_shr:2 row_mask:0xf bank_mask:0xf bound_ctrl:1
	v_mov_b32_dpp v181, v125 row_shr:1 row_mask:0xf bank_mask:0xf bound_ctrl:1
	s_and_saveexec_b64 s[0:1], s[40:41]
	s_cbranch_execz .LBB0_621
	s_waitcnt vmcnt(4)
	v_pk_fma_f32 v[194:195], v[146:147], v[194:195], v[158:159]
	v_pk_fma_f32 v[186:187], v[148:149], v[186:187], v[160:161]
	v_pk_fma_f32 v[192:193], v[150:151], v[192:193], v[194:195]
	v_pk_fma_f32 v[184:185], v[152:153], v[184:185], v[186:187]
	v_pk_fma_f32 v[192:193], v[56:57], v[154:155], v[192:193]
	v_pk_fma_f32 v[184:185], v[58:59], v[156:157], v[184:185]
	v_mul_f32_e32 v194, 0x3dd2d3e8, v192
	v_mul_f32_e32 v195, 0x3dd2d3e8, v193
	v_fmaak_f32 v194, v192, v194, 0x40135761
	v_fmaak_f32 v195, v193, v195, 0x40135761
	v_mul_f32_e32 v194, v192, v194
	v_mul_f32_e32 v195, v193, v195
	v_exp_f32_e32 v194, v194
	v_exp_f32_e32 v195, v195
	v_mul_f32_e32 v186, 0x3dd2d3e8, v184
	v_fmaak_f32 v186, v184, v186, 0x40135761
	v_add_f32_e32 v194, 1.0, v194
	v_add_f32_e32 v195, 1.0, v195
	v_rcp_f32_e32 v194, v194
	v_rcp_f32_e32 v195, v195
	s_waitcnt vmcnt(0)
	v_pk_fma_f32 v[190:191], v[130:131], v[190:191], v[142:143]
	v_mul_f32_e32 v186, v184, v186
	v_pk_fma_f32 v[188:189], v[134:135], v[188:189], v[190:191]
	v_pk_fma_f32 v[190:191], v[192:193], v[194:195], v[192:193] neg_lo:[1,0,0] neg_hi:[1,0,0]
	v_exp_f32_e32 v192, v186
	v_mul_f32_e32 v186, 0x3dd2d3e8, v185
	v_fmaak_f32 v186, v185, v186, 0x40135761
	v_mul_f32_e32 v186, v185, v186
	v_exp_f32_e32 v193, v186
	v_pk_fma_f32 v[188:189], v[122:123], v[138:139], v[188:189]
	v_pk_fma_f32 v[182:183], v[132:133], v[182:183], v[144:145]
	v_pk_mul_f32 v[186:187], v[188:189], v[190:191]
	v_add_f32_e32 v188, 1.0, v192
	v_add_f32_e32 v189, 1.0, v193
	v_rcp_f32_e32 v188, v188
	v_rcp_f32_e32 v189, v189
	v_pk_fma_f32 v[180:181], v[136:137], v[180:181], v[182:183]
	v_pk_fma_f32 v[182:183], v[184:185], v[188:189], v[184:185] neg_lo:[1,0,0] neg_hi:[1,0,0]
	v_pk_fma_f32 v[180:181], v[124:125], v[140:141], v[180:181]
	s_nop 0
	v_pk_mul_f32 v[180:181], v[180:181], v[182:183]
	v_cvt_pk_bf16_f32 v182, v186, v187
	v_cvt_pk_bf16_f32 v183, v180, v181
	v_mad_i64_i32 v[180:181], s[6:7], v172, s5, v[178:179]
	global_store_dwordx2 v[180:181], v[182:183], off offset:8

.LBB0_635:
	s_or_b64 exec, exec, s[0:1]
	v_readlane_b32 s2, v254, 39
	v_readlane_b32 s3, v254, 40
	s_and_saveexec_b64 s[0:1], s[2:3]
	s_cbranch_execz .LBB0_637
	v_readlane_b32 s2, v254, 29
	s_ashr_i32 s5, s4, 2
	v_readlane_b32 s3, v254, 30
	v_add_u32_e32 v144, s5, v202
	s_movk_i32 s42, 0x2c00
	v_mov_b64_e32 v[138:139], s[2:3]
	v_mad_i64_i32 v[130:131], s[6:7], v144, s42, v[138:139]
	v_lshlrev_b64 v[140:141], 1, v[176:177]
	v_lshl_add_u64 v[142:143], v[130:131], 0, v[140:141]
	v_cvt_pk_bf16_f32 v130, v68, v69
	v_cvt_pk_bf16_f32 v131, v70, v71
	v_cvt_pk_bf16_f32 v132, v56, v57
	v_cvt_pk_bf16_f32 v133, v58, v59
	global_store_dwordx4 v[142:143], v[130:133], off
	v_cvt_pk_bf16_f32 v134, v126, v127
	v_cvt_pk_bf16_f32 v135, v128, v129
	v_add_co_u32_e32 v130, vcc, s25, v142
	v_cvt_pk_bf16_f32 v136, v122, v123
	v_cvt_pk_bf16_f32 v137, v124, v125
	v_addc_co_u32_e32 v131, vcc, 0, v143, vcc
	global_store_dwordx4 v[130:131], v[134:137], off offset:1536
	v_add_u32_e32 v130, 4, v144
	v_mad_i64_i32 v[130:131], s[6:7], v130, s42, v[138:139]
	v_lshl_add_u64 v[142:143], v[130:131], 0, v[140:141]
	v_cvt_pk_bf16_f32 v130, v52, v53
	v_cvt_pk_bf16_f32 v131, v54, v55
	v_cvt_pk_bf16_f32 v132, v48, v49
	v_cvt_pk_bf16_f32 v133, v50, v51
	global_store_dwordx4 v[142:143], v[130:133], off
	v_cvt_pk_bf16_f32 v134, v118, v119
	v_cvt_pk_bf16_f32 v135, v120, v121
	v_add_co_u32_e32 v130, vcc, s25, v142
	v_cvt_pk_bf16_f32 v136, v114, v115
	v_cvt_pk_bf16_f32 v137, v116, v117
	v_addc_co_u32_e32 v131, vcc, 0, v143, vcc
	global_store_dwordx4 v[130:131], v[134:137], off offset:1536
	v_add_u32_e32 v130, 8, v144
	v_mad_i64_i32 v[130:131], s[6:7], v130, s42, v[138:139]
	v_lshl_add_u64 v[142:143], v[130:131], 0, v[140:141]
	v_cvt_pk_bf16_f32 v130, v44, v45
	v_cvt_pk_bf16_f32 v131, v46, v47
	v_cvt_pk_bf16_f32 v132, v40, v41
	v_cvt_pk_bf16_f32 v133, v42, v43
	global_store_dwordx4 v[142:143], v[130:133], off
	v_cvt_pk_bf16_f32 v134, v108, v109
	v_cvt_pk_bf16_f32 v135, v110, v111
	v_add_co_u32_e32 v130, vcc, s25, v142
	v_cvt_pk_bf16_f32 v136, v104, v105
	v_cvt_pk_bf16_f32 v137, v106, v107
	v_addc_co_u32_e32 v131, vcc, 0, v143, vcc
	global_store_dwordx4 v[130:131], v[134:137], off offset:1536
	v_add_u32_e32 v130, 12, v144
	v_mad_i64_i32 v[130:131], s[6:7], v130, s42, v[138:139]
	v_lshl_add_u64 v[142:143], v[130:131], 0, v[140:141]
	v_cvt_pk_bf16_f32 v130, v36, v37
	v_cvt_pk_bf16_f32 v131, v38, v39
	v_cvt_pk_bf16_f32 v132, v32, v33
	v_cvt_pk_bf16_f32 v133, v34, v35
	global_store_dwordx4 v[142:143], v[130:133], off
	s_add_i32 s5, s4, 0x80
	v_cvt_pk_bf16_f32 v134, v100, v101
	v_add_co_u32_e32 v130, vcc, s25, v142
	v_cvt_pk_bf16_f32 v135, v102, v103
	v_cvt_pk_bf16_f32 v136, v96, v97
	v_cvt_pk_bf16_f32 v137, v98, v99
	v_addc_co_u32_e32 v131, vcc, 0, v143, vcc
	s_ashr_i32 s5, s5, 2
	global_store_dwordx4 v[130:131], v[134:137], off offset:1536
	v_add_u32_e32 v130, s5, v202
	v_mad_i64_i32 v[130:131], s[6:7], v130, s42, v[138:139]
	v_lshl_add_u64 v[142:143], v[130:131], 0, v[140:141]
	v_cvt_pk_bf16_f32 v130, v28, v29
	v_cvt_pk_bf16_f32 v131, v30, v31
	v_cvt_pk_bf16_f32 v132, v24, v25
	v_cvt_pk_bf16_f32 v133, v26, v27
	global_store_dwordx4 v[142:143], v[130:133], off
	s_add_i32 s5, s4, 0x90
	v_cvt_pk_bf16_f32 v134, v92, v93
	v_add_co_u32_e32 v130, vcc, s25, v142
	v_cvt_pk_bf16_f32 v135, v94, v95
	v_cvt_pk_bf16_f32 v136, v88, v89
	v_cvt_pk_bf16_f32 v137, v90, v91
	v_addc_co_u32_e32 v131, vcc, 0, v143, vcc
	s_ashr_i32 s5, s5, 2
	global_store_dwordx4 v[130:131], v[134:137], off offset:1536
	v_add_u32_e32 v130, s5, v202
	v_mad_i64_i32 v[130:131], s[6:7], v130, s42, v[138:139]
	v_lshl_add_u64 v[142:143], v[130:131], 0, v[140:141]
	v_cvt_pk_bf16_f32 v130, v20, v21
	v_cvt_pk_bf16_f32 v131, v22, v23
	v_cvt_pk_bf16_f32 v132, v16, v17
	v_cvt_pk_bf16_f32 v133, v18, v19
	global_store_dwordx4 v[142:143], v[130:133], off
	s_add_i32 s5, s4, 0xa0
	v_cvt_pk_bf16_f32 v134, v84, v85
	v_add_co_u32_e32 v130, vcc, s25, v142
	v_cvt_pk_bf16_f32 v135, v86, v87
	v_cvt_pk_bf16_f32 v136, v80, v81
	v_cvt_pk_bf16_f32 v137, v82, v83
	v_addc_co_u32_e32 v131, vcc, 0, v143, vcc
	s_ashr_i32 s5, s5, 2
	global_store_dwordx4 v[130:131], v[134:137], off offset:1536
	v_add_u32_e32 v130, s5, v202
	v_mad_i64_i32 v[130:131], s[6:7], v130, s42, v[138:139]
	v_lshl_add_u64 v[142:143], v[130:131], 0, v[140:141]
	v_cvt_pk_bf16_f32 v130, v12, v13
	v_cvt_pk_bf16_f32 v131, v14, v15
	v_cvt_pk_bf16_f32 v132, v8, v9
	v_cvt_pk_bf16_f32 v133, v10, v11
	global_store_dwordx4 v[142:143], v[130:133], off
	s_addk_i32 s4, 0xb0
	v_cvt_pk_bf16_f32 v134, v76, v77
	v_add_co_u32_e32 v130, vcc, s25, v142
	v_cvt_pk_bf16_f32 v135, v78, v79
	v_cvt_pk_bf16_f32 v136, v72, v73
	v_cvt_pk_bf16_f32 v137, v74, v75
	v_addc_co_u32_e32 v131, vcc, 0, v143, vcc
	s_ashr_i32 s4, s4, 2
	global_store_dwordx4 v[130:131], v[134:137], off offset:1536
	v_add_u32_e32 v130, s4, v202
	v_mad_i64_i32 v[130:131], s[4:5], v130, s42, v[138:139]
	v_lshl_add_u64 v[138:139], v[130:131], 0, v[140:141]
	v_cvt_pk_bf16_f32 v130, v4, v5
	v_cvt_pk_bf16_f32 v131, v6, v7
	v_cvt_pk_bf16_f32 v132, v0, v1
	v_cvt_pk_bf16_f32 v133, v2, v3
	global_store_dwordx4 v[138:139], v[130:133], off
	v_cvt_pk_bf16_f32 v134, v64, v65
	v_cvt_pk_bf16_f32 v135, v66, v67
	v_add_co_u32_e32 v130, vcc, 0x1000, v138
	v_cvt_pk_bf16_f32 v136, v60, v61
	v_cvt_pk_bf16_f32 v137, v62, v63
	v_addc_co_u32_e32 v131, vcc, 0, v139, vcc
	global_store_dwordx4 v[130:131], v[134:137], off offset:1536
